# layer-0 out-projection fused epilogue: f32 residual rows prefetched in 3 batches (8+4+2 blocks) into free registers instead of one exposed HBM round trip per block
# baseline (speedup 1.0000x reference)
.LBB0_1002:
	s_add_u32 s16, s0, 0x1f400000
	s_addc_u32 s17, s1, 0
	s_lshl_b32 s2, s7, 5
	s_lshl_b32 s3, s12, 8
	s_or_b32 s2, s3, s2
	v_lshrrev_b32_e32 v92, 1, v164
	s_cmp_lg_u64 s[14:15], 0
	v_and_or_b32 v216, v92, 24, s2
	s_cselect_b64 s[18:19], -1, 0
	s_and_b64 vcc, exec, s[18:19]
	v_ashrrev_i32_e32 v217, 31, v216
	s_barrier
	s_cbranch_vccnz .Lg2_f32pre
	s_lshl_b32 s2, s6, 8
	s_add_i32 s2, s2, s43
	v_or_b32_e32 v92, s2, v166
	v_ashrrev_i32_e32 v93, 31, v92
	v_lshl_add_u64 v[94:95], v[216:217], 1, s[16:17]
	v_lshlrev_b64 v[108:109], 11, v[92:93]
	v_lshl_add_u64 v[108:109], v[94:95], 0, v[108:109]
	global_load_dwordx4 v[204:207], v[108:109], off
	global_load_dwordx4 v[200:203], v[108:109], off offset:256
	v_or_b32_e32 v108, 16, v92
	v_ashrrev_i32_e32 v109, 31, v108
	v_lshlrev_b64 v[108:109], 11, v[108:109]
	v_lshl_add_u64 v[108:109], v[94:95], 0, v[108:109]
	global_load_dwordx4 v[196:199], v[108:109], off
	global_load_dwordx4 v[192:195], v[108:109], off offset:256
	v_or_b32_e32 v108, 32, v92
	v_ashrrev_i32_e32 v109, 31, v108
	v_lshlrev_b64 v[108:109], 11, v[108:109]
	v_lshl_add_u64 v[108:109], v[94:95], 0, v[108:109]
	global_load_dwordx4 v[188:191], v[108:109], off
	global_load_dwordx4 v[184:187], v[108:109], off offset:256
	v_or_b32_e32 v108, 48, v92
	v_ashrrev_i32_e32 v109, 31, v108
	v_lshlrev_b64 v[108:109], 11, v[108:109]
	v_lshl_add_u64 v[108:109], v[94:95], 0, v[108:109]
	global_load_dwordx4 v[172:175], v[108:109], off
	global_load_dwordx4 v[160:163], v[108:109], off offset:256
	v_add_u32_e32 v108, 0x80, v92
	v_ashrrev_i32_e32 v109, 31, v108
	v_lshlrev_b64 v[108:109], 11, v[108:109]
	v_lshl_add_u64 v[108:109], v[94:95], 0, v[108:109]
	global_load_dwordx4 v[156:159], v[108:109], off
	global_load_dwordx4 v[152:155], v[108:109], off offset:256
	v_add_u32_e32 v108, 0x90, v92
	v_ashrrev_i32_e32 v109, 31, v108
	v_lshlrev_b64 v[108:109], 11, v[108:109]
	v_lshl_add_u64 v[108:109], v[94:95], 0, v[108:109]
	global_load_dwordx4 v[148:151], v[108:109], off
	global_load_dwordx4 v[136:139], v[108:109], off offset:256
	v_add_u32_e32 v108, 0xa0, v92
	v_add_u32_e32 v92, 0xb0, v92
	v_ashrrev_i32_e32 v109, 31, v108
	v_ashrrev_i32_e32 v93, 31, v92
	v_lshlrev_b64 v[108:109], 11, v[108:109]
	v_lshlrev_b64 v[92:93], 11, v[92:93]
	v_lshl_add_u64 v[108:109], v[94:95], 0, v[108:109]
	v_lshl_add_u64 v[92:93], v[94:95], 0, v[92:93]
	global_load_dwordx4 v[132:135], v[108:109], off
	global_load_dwordx4 v[112:115], v[108:109], off offset:256
	s_nop 0
	global_load_dwordx4 v[108:111], v[92:93], off
	s_nop 0
	global_load_dwordx4 v[92:95], v[92:93], off offset:256
	s_branch .LBB0_1004
.Lg2_f32pre:
	s_lshl_b32 s99, s6, 8
	v_add_u32_e32 v240, s99, v232
	v_lshlrev_b32_e32 v240, 12, v240
	v_lshl_add_u32 v240, v216, 2, v240
	s_add_u32 s100, s14, 0x0
	s_addc_u32 s101, s15, 0
	global_load_dwordx4 v[200:203], v240, s[100:101] offset:16
	global_load_dwordx4 v[204:207], v240, s[100:101]
	global_load_dwordx4 v[192:195], v240, s[100:101] offset:528
	global_load_dwordx4 v[196:199], v240, s[100:101] offset:512
	s_add_u32 s100, s14, 0x10000
	s_addc_u32 s101, s15, 0
	global_load_dwordx4 v[184:187], v240, s[100:101] offset:16
	global_load_dwordx4 v[188:191], v240, s[100:101]
	global_load_dwordx4 v[160:163], v240, s[100:101] offset:528
	global_load_dwordx4 v[172:175], v240, s[100:101] offset:512
	s_add_u32 s100, s14, 0x20000
	s_addc_u32 s101, s15, 0
	global_load_dwordx4 v[152:155], v240, s[100:101] offset:16
	global_load_dwordx4 v[156:159], v240, s[100:101]
	global_load_dwordx4 v[136:139], v240, s[100:101] offset:528
	global_load_dwordx4 v[148:151], v240, s[100:101] offset:512
	s_add_u32 s100, s14, 0x30000
	s_addc_u32 s101, s15, 0
	global_load_dwordx4 v[112:115], v240, s[100:101] offset:16
	global_load_dwordx4 v[132:135], v240, s[100:101]
	global_load_dwordx4 v[92:95], v240, s[100:101] offset:528
	global_load_dwordx4 v[108:111], v240, s[100:101] offset:512

.LBB0_1041:
	v_lshl_add_u32 v238, v168, 2, v208
	s_and_saveexec_b64 s[6:7], s[2:3]
	ds_write_b32 v238, v167 offset:8192
	s_or_b64 exec, exec, s[6:7]
	v_mov_b32_e32 v164, s8
	v_mov_b32_e32 v165, s9
	s_waitcnt lgkmcnt(0)
	s_barrier
	v_lshl_add_u64 v[168:169], v[216:217], 2, v[164:165]
	global_load_dwordx4 v[176:179], v[168:169], off offset:16
	global_load_dwordx4 v[180:183], v[168:169], off
	global_load_dwordx4 v[164:167], v[168:169], off offset:528
	s_nop 0
	global_load_dwordx4 v[168:171], v[168:169], off offset:512
	v_lshl_add_u32 v233, v232, 2, v208
	ds_read_b32 v222, v233 offset:8192
	v_add_u32_e32 v218, s26, v232
	v_ashrrev_i32_e32 v219, 31, v218
	v_lshlrev_b64 v[208:209], 10, v[218:219]
	v_lshl_add_u64 v[226:227], v[208:209], 0, v[216:217]
	v_cndmask_b32_e64 v208, 0, 1, s[18:19]
	v_cmp_ne_u32_e64 s[6:7], 1, v208
	s_andn2_b64 vcc, exec, s[18:19]
	v_lshl_add_u64 v[224:225], v[226:227], 2, s[14:15]
	s_cbranch_vccnz .LBB0_1045
	s_waitcnt vmcnt(4)
	s_nop 1
	v_mov_b32_e32 v208, v200
	v_mov_b32_e32 v209, v201
	v_mov_b32_e32 v210, v202
	v_mov_b32_e32 v211, v203
	v_mov_b32_e32 v212, v204
	v_mov_b32_e32 v213, v205
	v_mov_b32_e32 v214, v206
	v_mov_b32_e32 v215, v207
	s_cbranch_execz .LBB0_1046
	s_branch .LBB0_1047

.LBB0_1047:
	s_waitcnt vmcnt(0)
	v_mov_b32_e32 v204, 0x358637bd
	s_waitcnt lgkmcnt(0)
	v_fmac_f32_e32 v204, 0x3a800000, v222
	s_mov_b32 s8, 0x800000
	v_mul_f32_e32 v205, 0x4b800000, v204
	v_cmp_gt_f32_e32 vcc, s8, v204
	s_nop 1
	v_cndmask_b32_e32 v204, v204, v205, vcc
	v_rsq_f32_e32 v204, v204
	s_nop 0
	v_mul_f32_e32 v205, 0x45800000, v204
	v_cndmask_b32_e32 v222, v204, v205, vcc
	v_pk_mul_f32 v[144:145], v[144:145], v[222:223] op_sel_hi:[1,0]
	v_pk_mul_f32 v[146:147], v[146:147], v[222:223] op_sel_hi:[1,0]
	v_pk_mul_f32 v[140:141], v[140:141], v[222:223] op_sel_hi:[1,0]
	v_pk_mul_f32 v[142:143], v[142:143], v[222:223] op_sel_hi:[1,0]
	v_pk_fma_f32 v[204:205], v[182:183], v[146:147], v[214:215]
	v_pk_fma_f32 v[206:207], v[180:181], v[144:145], v[212:213]
	v_pk_fma_f32 v[210:211], v[178:179], v[142:143], v[210:211]
	v_pk_fma_f32 v[208:209], v[176:177], v[140:141], v[208:209]
	v_lshl_add_u64 v[212:213], v[226:227], 1, s[16:17]
	s_and_b64 vcc, exec, s[6:7]
	v_cvt_pk_bf16_f32 v140, v206, v207
	v_cvt_pk_bf16_f32 v141, v204, v205
	v_cvt_pk_bf16_f32 v142, v208, v209
	v_cvt_pk_bf16_f32 v143, v210, v211
	global_store_dwordx4 v[212:213], v[140:143], off
	s_cbranch_vccnz .LBB0_1049
	s_nop 1
	v_mov_b32_e32 v140, v192
	v_mov_b32_e32 v141, v193
	v_mov_b32_e32 v142, v194
	v_mov_b32_e32 v143, v195
	v_mov_b32_e32 v144, v196
	v_mov_b32_e32 v145, v197
	v_mov_b32_e32 v146, v198
	v_mov_b32_e32 v147, v199
	v_mov_b32_e32 v223, v222
	s_cbranch_execz .LBB0_1050
	s_branch .LBB0_1051

.LBB0_1051:
	v_mov_b32_e32 v200, v222
	v_mov_b32_e32 v201, v222
	v_pk_mul_f32 v[130:131], v[130:131], v[200:201]
	v_pk_mul_f32 v[128:129], v[128:129], v[222:223]
	v_pk_mul_f32 v[126:127], v[126:127], v[200:201]
	v_pk_mul_f32 v[124:125], v[124:125], v[222:223]
	s_nop 0
	v_pk_fma_f32 v[146:147], v[170:171], v[130:131], v[146:147]
	v_pk_fma_f32 v[144:145], v[168:169], v[128:129], v[144:145]
	v_pk_fma_f32 v[142:143], v[166:167], v[126:127], v[142:143]
	v_pk_fma_f32 v[200:201], v[164:165], v[124:125], v[140:141]
	v_cvt_pk_bf16_f32 v124, v144, v145
	v_cvt_pk_bf16_f32 v125, v146, v147
	v_add3_u32 v140, s26, v232, 16
	v_cvt_pk_bf16_f32 v126, v200, v201
	v_cvt_pk_bf16_f32 v127, v142, v143
	ds_read_b32 v214, v233 offset:8256
	v_ashrrev_i32_e32 v141, 31, v140
	global_store_dwordx4 v[212:213], v[124:127], off offset:256
	s_and_b64 vcc, exec, s[6:7]
	s_nop 0
	v_lshlrev_b64 v[124:125], 10, v[140:141]
	v_lshl_add_u64 v[212:213], v[124:125], 0, v[216:217]
	v_lshl_add_u64 v[202:203], v[212:213], 2, s[14:15]
	s_cbranch_vccnz .LBB0_1053
	s_nop 1
	v_mov_b32_e32 v124, v184
	v_mov_b32_e32 v125, v185
	v_mov_b32_e32 v126, v186
	v_mov_b32_e32 v127, v187
	v_mov_b32_e32 v128, v188
	v_mov_b32_e32 v129, v189
	v_mov_b32_e32 v130, v190
	v_mov_b32_e32 v131, v191
	s_cbranch_execz .LBB0_1054
	s_branch .LBB0_1055

.LBB0_1055:
	v_mov_b32_e32 v196, 0x358637bd
	s_waitcnt lgkmcnt(0)
	v_fmac_f32_e32 v196, 0x3a800000, v214
	s_mov_b32 s8, 0x800000
	v_mul_f32_e32 v197, 0x4b800000, v196
	v_cmp_gt_f32_e32 vcc, s8, v196
	v_lshl_add_u64 v[198:199], v[212:213], 1, s[16:17]
	s_nop 0
	v_cndmask_b32_e32 v196, v196, v197, vcc
	v_rsq_f32_e32 v196, v196
	s_nop 0
	v_mul_f32_e32 v197, 0x45800000, v196
	v_cndmask_b32_e32 v196, v196, v197, vcc
	v_pk_mul_f32 v[120:121], v[120:121], v[196:197] op_sel_hi:[1,0]
	v_pk_mul_f32 v[122:123], v[122:123], v[196:197] op_sel_hi:[1,0]
	v_pk_mul_f32 v[116:117], v[116:117], v[196:197] op_sel_hi:[1,0]
	v_pk_mul_f32 v[118:119], v[118:119], v[196:197] op_sel_hi:[1,0]
	s_nop 0
	v_pk_fma_f32 v[130:131], v[182:183], v[122:123], v[130:131]
	v_pk_fma_f32 v[128:129], v[180:181], v[120:121], v[128:129]
	v_pk_fma_f32 v[126:127], v[178:179], v[118:119], v[126:127]
	v_pk_fma_f32 v[124:125], v[176:177], v[116:117], v[124:125]
	s_and_b64 vcc, exec, s[6:7]
	v_cvt_pk_bf16_f32 v116, v128, v129
	v_cvt_pk_bf16_f32 v117, v130, v131
	v_cvt_pk_bf16_f32 v118, v124, v125
	v_cvt_pk_bf16_f32 v119, v126, v127
	global_store_dwordx4 v[198:199], v[116:119], off
	s_cbranch_vccnz .LBB0_1057
	s_nop 1
	v_mov_b32_e32 v116, v160
	v_mov_b32_e32 v117, v161
	v_mov_b32_e32 v118, v162
	v_mov_b32_e32 v119, v163
	v_mov_b32_e32 v120, v172
	v_mov_b32_e32 v121, v173
	v_mov_b32_e32 v122, v174
	v_mov_b32_e32 v123, v175
	v_mov_b32_e32 v197, v196
	s_cbranch_execz .LBB0_1058
	s_branch .LBB0_1059

.LBB0_1059:
	v_mov_b32_e32 v192, v196
	v_mov_b32_e32 v193, v196
	v_pk_mul_f32 v[106:107], v[106:107], v[192:193]
	v_pk_mul_f32 v[104:105], v[104:105], v[196:197]
	v_pk_mul_f32 v[102:103], v[102:103], v[192:193]
	v_pk_mul_f32 v[100:101], v[100:101], v[196:197]
	s_nop 0
	v_pk_fma_f32 v[122:123], v[170:171], v[106:107], v[122:123]
	v_pk_fma_f32 v[120:121], v[168:169], v[104:105], v[120:121]
	v_pk_fma_f32 v[118:119], v[166:167], v[102:103], v[118:119]
	v_pk_fma_f32 v[192:193], v[164:165], v[100:101], v[116:117]
	v_cvt_pk_bf16_f32 v100, v120, v121
	v_cvt_pk_bf16_f32 v101, v122, v123
	v_add3_u32 v116, s26, v232, 32
	v_cvt_pk_bf16_f32 v102, v192, v193
	v_cvt_pk_bf16_f32 v103, v118, v119
	global_store_dwordx4 v[198:199], v[100:103], off offset:256
	ds_read_b32 v198, v233 offset:8320
	v_ashrrev_i32_e32 v117, 31, v116
	v_lshlrev_b64 v[100:101], 10, v[116:117]
	v_lshl_add_u64 v[196:197], v[100:101], 0, v[216:217]
	s_and_b64 vcc, exec, s[6:7]
	v_lshl_add_u64 v[194:195], v[196:197], 2, s[14:15]
	s_cbranch_vccnz .LBB0_1061
	s_nop 1
	v_mov_b32_e32 v100, v152
	v_mov_b32_e32 v101, v153
	v_mov_b32_e32 v102, v154
	v_mov_b32_e32 v103, v155
	v_mov_b32_e32 v104, v156
	v_mov_b32_e32 v105, v157
	v_mov_b32_e32 v106, v158
	v_mov_b32_e32 v107, v159
	s_cbranch_execz .LBB0_1062
	s_branch .LBB0_1063

.LBB0_1063:
	v_mov_b32_e32 v188, 0x358637bd
	s_waitcnt lgkmcnt(0)
	v_fmac_f32_e32 v188, 0x3a800000, v198
	s_mov_b32 s8, 0x800000
	v_mul_f32_e32 v189, 0x4b800000, v188
	v_cmp_gt_f32_e32 vcc, s8, v188
	v_lshl_add_u64 v[190:191], v[196:197], 1, s[16:17]
	s_nop 0
	v_cndmask_b32_e32 v188, v188, v189, vcc
	v_rsq_f32_e32 v188, v188
	s_nop 0
	v_mul_f32_e32 v189, 0x45800000, v188
	v_cndmask_b32_e32 v188, v188, v189, vcc
	v_pk_mul_f32 v[96:97], v[96:97], v[188:189] op_sel_hi:[1,0]
	v_pk_mul_f32 v[98:99], v[98:99], v[188:189] op_sel_hi:[1,0]
	v_pk_mul_f32 v[88:89], v[88:89], v[188:189] op_sel_hi:[1,0]
	v_pk_mul_f32 v[90:91], v[90:91], v[188:189] op_sel_hi:[1,0]
	s_nop 0
	v_pk_fma_f32 v[106:107], v[182:183], v[98:99], v[106:107]
	v_pk_fma_f32 v[104:105], v[180:181], v[96:97], v[104:105]
	v_pk_fma_f32 v[102:103], v[178:179], v[90:91], v[102:103]
	v_pk_fma_f32 v[100:101], v[176:177], v[88:89], v[100:101]
	s_and_b64 vcc, exec, s[6:7]
	v_cvt_pk_bf16_f32 v88, v104, v105
	v_cvt_pk_bf16_f32 v89, v106, v107
	v_cvt_pk_bf16_f32 v90, v100, v101
	v_cvt_pk_bf16_f32 v91, v102, v103
	global_store_dwordx4 v[190:191], v[88:91], off
	s_cbranch_vccnz .LBB0_1065
	s_nop 1
	v_mov_b32_e32 v88, v136
	v_mov_b32_e32 v89, v137
	v_mov_b32_e32 v90, v138
	v_mov_b32_e32 v91, v139
	v_mov_b32_e32 v96, v148
	v_mov_b32_e32 v97, v149
	v_mov_b32_e32 v98, v150
	v_mov_b32_e32 v99, v151
	v_mov_b32_e32 v189, v188
	s_cbranch_execz .LBB0_1066
	s_branch .LBB0_1067

.LBB0_1067:
	v_mov_b32_e32 v184, v188
	v_mov_b32_e32 v185, v188
	v_pk_mul_f32 v[86:87], v[86:87], v[184:185]
	v_pk_mul_f32 v[84:85], v[84:85], v[188:189]
	v_pk_mul_f32 v[82:83], v[82:83], v[184:185]
	v_pk_mul_f32 v[80:81], v[80:81], v[188:189]
	s_nop 0
	v_pk_fma_f32 v[98:99], v[170:171], v[86:87], v[98:99]
	v_pk_fma_f32 v[96:97], v[168:169], v[84:85], v[96:97]
	v_pk_fma_f32 v[90:91], v[166:167], v[82:83], v[90:91]
	v_pk_fma_f32 v[184:185], v[164:165], v[80:81], v[88:89]
	v_cvt_pk_bf16_f32 v80, v96, v97
	v_cvt_pk_bf16_f32 v81, v98, v99
	v_add3_u32 v88, s26, v232, 48
	v_cvt_pk_bf16_f32 v82, v184, v185
	v_cvt_pk_bf16_f32 v83, v90, v91
	global_store_dwordx4 v[190:191], v[80:83], off offset:256
	ds_read_b32 v190, v233 offset:8384
	v_ashrrev_i32_e32 v89, 31, v88
	v_lshlrev_b64 v[80:81], 10, v[88:89]
	v_lshl_add_u64 v[188:189], v[80:81], 0, v[216:217]
	s_and_b64 vcc, exec, s[6:7]
	v_lshl_add_u64 v[186:187], v[188:189], 2, s[14:15]
	s_cbranch_vccnz .LBB0_1069
	s_nop 1
	v_mov_b32_e32 v80, v112
	v_mov_b32_e32 v81, v113
	v_mov_b32_e32 v82, v114
	v_mov_b32_e32 v83, v115
	v_mov_b32_e32 v84, v132
	v_mov_b32_e32 v85, v133
	v_mov_b32_e32 v86, v134
	v_mov_b32_e32 v87, v135
	s_cbranch_execz .LBB0_1070
	s_branch .LBB0_1071

.LBB0_1071:
	v_mov_b32_e32 v172, 0x358637bd
	s_waitcnt lgkmcnt(0)
	v_fmac_f32_e32 v172, 0x3a800000, v190
	s_mov_b32 s8, 0x800000
	v_mul_f32_e32 v173, 0x4b800000, v172
	v_cmp_gt_f32_e32 vcc, s8, v172
	v_lshl_add_u64 v[174:175], v[188:189], 1, s[16:17]
	s_nop 0
	v_cndmask_b32_e32 v172, v172, v173, vcc
	v_rsq_f32_e32 v172, v172
	s_nop 0
	v_mul_f32_e32 v173, 0x45800000, v172
	v_cndmask_b32_e32 v172, v172, v173, vcc
	v_pk_mul_f32 v[76:77], v[76:77], v[172:173] op_sel_hi:[1,0]
	v_pk_mul_f32 v[78:79], v[78:79], v[172:173] op_sel_hi:[1,0]
	v_pk_mul_f32 v[72:73], v[72:73], v[172:173] op_sel_hi:[1,0]
	v_pk_mul_f32 v[74:75], v[74:75], v[172:173] op_sel_hi:[1,0]
	s_nop 0
	v_pk_fma_f32 v[86:87], v[182:183], v[78:79], v[86:87]
	v_pk_fma_f32 v[84:85], v[180:181], v[76:77], v[84:85]
	v_pk_fma_f32 v[82:83], v[178:179], v[74:75], v[82:83]
	v_pk_fma_f32 v[80:81], v[176:177], v[72:73], v[80:81]
	s_and_b64 vcc, exec, s[6:7]
	v_cvt_pk_bf16_f32 v72, v84, v85
	v_cvt_pk_bf16_f32 v73, v86, v87
	v_cvt_pk_bf16_f32 v74, v80, v81
	v_cvt_pk_bf16_f32 v75, v82, v83
	global_store_dwordx4 v[174:175], v[72:75], off
	s_cbranch_vccnz .LBB0_1073
	s_nop 1
	v_mov_b32_e32 v72, v92
	v_mov_b32_e32 v73, v93
	v_mov_b32_e32 v74, v94
	v_mov_b32_e32 v75, v95
	v_mov_b32_e32 v76, v108
	v_mov_b32_e32 v77, v109
	v_mov_b32_e32 v78, v110
	v_mov_b32_e32 v79, v111
	v_mov_b32_e32 v173, v172
	s_cbranch_execz .LBB0_1074
	s_branch .LBB0_1075

.LBB0_1075:
	v_mov_b32_e32 v160, v172
	v_mov_b32_e32 v161, v172
	v_pk_mul_f32 v[70:71], v[70:71], v[160:161]
	v_pk_mul_f32 v[68:69], v[68:69], v[172:173]
	v_pk_mul_f32 v[66:67], v[66:67], v[160:161]
	v_pk_mul_f32 v[64:65], v[64:65], v[172:173]
	s_nop 0
	v_pk_fma_f32 v[78:79], v[170:171], v[70:71], v[78:79]
	v_pk_fma_f32 v[76:77], v[168:169], v[68:69], v[76:77]
	v_pk_fma_f32 v[74:75], v[166:167], v[66:67], v[74:75]
	v_pk_fma_f32 v[160:161], v[164:165], v[64:65], v[72:73]
	v_cvt_pk_bf16_f32 v64, v76, v77
	v_cvt_pk_bf16_f32 v65, v78, v79
	v_add_u32_e32 v72, 0x80, v218
	v_cvt_pk_bf16_f32 v66, v160, v161
	v_cvt_pk_bf16_f32 v67, v74, v75
	global_store_dwordx4 v[174:175], v[64:67], off offset:256
	ds_read_b32 v174, v233 offset:8704
	v_ashrrev_i32_e32 v73, 31, v72
	v_lshlrev_b64 v[64:65], 10, v[72:73]
	v_lshl_add_u64 v[172:173], v[64:65], 0, v[216:217]
	s_and_b64 vcc, exec, s[6:7]
	v_lshl_add_u64 v[162:163], v[172:173], 2, s[14:15]
	s_cbranch_vccnz .LBB0_1077
	s_add_u32 s100, s14, 0x80000
	s_addc_u32 s101, s15, 0
	global_load_dwordx4 v[152:155], v240, s[100:101] offset:16
	global_load_dwordx4 v[156:159], v240, s[100:101]
	global_load_dwordx4 v[136:139], v240, s[100:101] offset:528
	global_load_dwordx4 v[148:151], v240, s[100:101] offset:512
	s_add_u32 s100, s14, 0x90000
	s_addc_u32 s101, s15, 0
	global_load_dwordx4 v[112:115], v240, s[100:101] offset:16
	global_load_dwordx4 v[132:135], v240, s[100:101]
	global_load_dwordx4 v[92:95], v240, s[100:101] offset:528
	global_load_dwordx4 v[108:111], v240, s[100:101] offset:512
	s_waitcnt vmcnt(6)
	s_nop 1
	v_mov_b32_e32 v64, v152
	v_mov_b32_e32 v65, v153
	v_mov_b32_e32 v66, v154
	v_mov_b32_e32 v67, v155
	v_mov_b32_e32 v68, v156
	v_mov_b32_e32 v69, v157
	v_mov_b32_e32 v70, v158
	v_mov_b32_e32 v71, v159
	s_cbranch_execz .LBB0_1078
	s_branch .LBB0_1079

.LBB0_1079:
	v_mov_b32_e32 v156, 0x358637bd
	s_waitcnt lgkmcnt(0)
	v_fmac_f32_e32 v156, 0x3a800000, v174
	s_mov_b32 s8, 0x800000
	v_mul_f32_e32 v157, 0x4b800000, v156
	v_cmp_gt_f32_e32 vcc, s8, v156
	v_lshl_add_u64 v[158:159], v[172:173], 1, s[16:17]
	s_nop 0
	v_cndmask_b32_e32 v156, v156, v157, vcc
	v_rsq_f32_e32 v156, v156
	s_nop 0
	v_mul_f32_e32 v157, 0x45800000, v156
	v_cndmask_b32_e32 v156, v156, v157, vcc
	v_pk_mul_f32 v[60:61], v[60:61], v[156:157] op_sel_hi:[1,0]
	v_pk_mul_f32 v[62:63], v[62:63], v[156:157] op_sel_hi:[1,0]
	v_pk_mul_f32 v[56:57], v[56:57], v[156:157] op_sel_hi:[1,0]
	v_pk_mul_f32 v[58:59], v[58:59], v[156:157] op_sel_hi:[1,0]
	s_nop 0
	v_pk_fma_f32 v[70:71], v[182:183], v[62:63], v[70:71]
	v_pk_fma_f32 v[68:69], v[180:181], v[60:61], v[68:69]
	v_pk_fma_f32 v[66:67], v[178:179], v[58:59], v[66:67]
	v_pk_fma_f32 v[64:65], v[176:177], v[56:57], v[64:65]
	s_and_b64 vcc, exec, s[6:7]
	v_cvt_pk_bf16_f32 v56, v68, v69
	v_cvt_pk_bf16_f32 v57, v70, v71
	v_cvt_pk_bf16_f32 v58, v64, v65
	v_cvt_pk_bf16_f32 v59, v66, v67
	global_store_dwordx4 v[158:159], v[56:59], off
	s_cbranch_vccnz .LBB0_1081
	s_waitcnt vmcnt(5)
	s_nop 1
	v_mov_b32_e32 v56, v136
	v_mov_b32_e32 v57, v137
	v_mov_b32_e32 v58, v138
	v_mov_b32_e32 v59, v139
	v_mov_b32_e32 v60, v148
	v_mov_b32_e32 v61, v149
	v_mov_b32_e32 v62, v150
	v_mov_b32_e32 v63, v151
	v_mov_b32_e32 v157, v156
	s_cbranch_execz .LBB0_1082
	s_branch .LBB0_1083

.LBB0_1083:
	v_mov_b32_e32 v152, v156
	v_mov_b32_e32 v153, v156
	v_pk_mul_f32 v[54:55], v[54:55], v[152:153]
	v_pk_mul_f32 v[52:53], v[52:53], v[156:157]
	v_pk_mul_f32 v[50:51], v[50:51], v[152:153]
	v_pk_mul_f32 v[48:49], v[48:49], v[156:157]
	s_nop 0
	v_pk_fma_f32 v[62:63], v[170:171], v[54:55], v[62:63]
	v_pk_fma_f32 v[60:61], v[168:169], v[52:53], v[60:61]
	v_pk_fma_f32 v[58:59], v[166:167], v[50:51], v[58:59]
	v_pk_fma_f32 v[152:153], v[164:165], v[48:49], v[56:57]
	v_cvt_pk_bf16_f32 v48, v60, v61
	v_cvt_pk_bf16_f32 v49, v62, v63
	v_add_u32_e32 v56, 0x90, v218
	v_cvt_pk_bf16_f32 v50, v152, v153
	v_cvt_pk_bf16_f32 v51, v58, v59
	global_store_dwordx4 v[158:159], v[48:51], off offset:256
	ds_read_b32 v158, v233 offset:8768
	v_ashrrev_i32_e32 v57, 31, v56
	v_lshlrev_b64 v[48:49], 10, v[56:57]
	v_lshl_add_u64 v[156:157], v[48:49], 0, v[216:217]
	s_and_b64 vcc, exec, s[6:7]
	v_lshl_add_u64 v[154:155], v[156:157], 2, s[14:15]
	s_cbranch_vccnz .LBB0_1085
	s_waitcnt vmcnt(4)
	s_nop 1
	v_mov_b32_e32 v48, v112
	v_mov_b32_e32 v49, v113
	v_mov_b32_e32 v50, v114
	v_mov_b32_e32 v51, v115
	v_mov_b32_e32 v52, v132
	v_mov_b32_e32 v53, v133
	v_mov_b32_e32 v54, v134
	v_mov_b32_e32 v55, v135
	s_cbranch_execz .LBB0_1086
	s_branch .LBB0_1087

.LBB0_1087:
	v_mov_b32_e32 v148, 0x358637bd
	s_waitcnt lgkmcnt(0)
	v_fmac_f32_e32 v148, 0x3a800000, v158
	s_mov_b32 s8, 0x800000
	v_mul_f32_e32 v149, 0x4b800000, v148
	v_cmp_gt_f32_e32 vcc, s8, v148
	v_lshl_add_u64 v[150:151], v[156:157], 1, s[16:17]
	s_nop 0
	v_cndmask_b32_e32 v148, v148, v149, vcc
	v_rsq_f32_e32 v148, v148
	s_nop 0
	v_mul_f32_e32 v149, 0x45800000, v148
	v_cndmask_b32_e32 v148, v148, v149, vcc
	v_pk_mul_f32 v[44:45], v[44:45], v[148:149] op_sel_hi:[1,0]
	v_pk_mul_f32 v[46:47], v[46:47], v[148:149] op_sel_hi:[1,0]
	v_pk_mul_f32 v[40:41], v[40:41], v[148:149] op_sel_hi:[1,0]
	v_pk_mul_f32 v[42:43], v[42:43], v[148:149] op_sel_hi:[1,0]
	s_nop 0
	v_pk_fma_f32 v[54:55], v[182:183], v[46:47], v[54:55]
	v_pk_fma_f32 v[52:53], v[180:181], v[44:45], v[52:53]
	v_pk_fma_f32 v[50:51], v[178:179], v[42:43], v[50:51]
	v_pk_fma_f32 v[48:49], v[176:177], v[40:41], v[48:49]
	s_and_b64 vcc, exec, s[6:7]
	v_cvt_pk_bf16_f32 v40, v52, v53
	v_cvt_pk_bf16_f32 v41, v54, v55
	v_cvt_pk_bf16_f32 v42, v48, v49
	v_cvt_pk_bf16_f32 v43, v50, v51
	global_store_dwordx4 v[150:151], v[40:43], off
	s_cbranch_vccnz .LBB0_1089
	s_waitcnt vmcnt(3)
	s_nop 1
	v_mov_b32_e32 v40, v92
	v_mov_b32_e32 v41, v93
	v_mov_b32_e32 v42, v94
	v_mov_b32_e32 v43, v95
	v_mov_b32_e32 v44, v108
	v_mov_b32_e32 v45, v109
	v_mov_b32_e32 v46, v110
	v_mov_b32_e32 v47, v111
	v_mov_b32_e32 v149, v148
	s_cbranch_execz .LBB0_1090
	s_branch .LBB0_1091

.LBB0_1091:
	v_mov_b32_e32 v136, v148
	v_mov_b32_e32 v137, v148
	v_pk_mul_f32 v[38:39], v[38:39], v[136:137]
	v_pk_mul_f32 v[36:37], v[36:37], v[148:149]
	v_pk_mul_f32 v[34:35], v[34:35], v[136:137]
	v_pk_mul_f32 v[32:33], v[32:33], v[148:149]
	s_nop 0
	v_pk_fma_f32 v[46:47], v[170:171], v[38:39], v[46:47]
	v_pk_fma_f32 v[44:45], v[168:169], v[36:37], v[44:45]
	v_pk_fma_f32 v[42:43], v[166:167], v[34:35], v[42:43]
	v_pk_fma_f32 v[136:137], v[164:165], v[32:33], v[40:41]
	v_cvt_pk_bf16_f32 v32, v44, v45
	v_cvt_pk_bf16_f32 v33, v46, v47
	v_add_u32_e32 v40, 0xa0, v218
	v_cvt_pk_bf16_f32 v34, v136, v137
	v_cvt_pk_bf16_f32 v35, v42, v43
	global_store_dwordx4 v[150:151], v[32:35], off offset:256
	ds_read_b32 v150, v233 offset:8832
	v_ashrrev_i32_e32 v41, 31, v40
	v_lshlrev_b64 v[32:33], 10, v[40:41]
	v_lshl_add_u64 v[148:149], v[32:33], 0, v[216:217]
	s_and_b64 vcc, exec, s[6:7]
	v_lshl_add_u64 v[138:139], v[148:149], 2, s[14:15]
	s_cbranch_vccnz .LBB0_1093
	s_add_u32 s100, s14, 0xa0000
	s_addc_u32 s101, s15, 0
	global_load_dwordx4 v[112:115], v240, s[100:101] offset:16
	global_load_dwordx4 v[132:135], v240, s[100:101]
	global_load_dwordx4 v[92:95], v240, s[100:101] offset:528
	global_load_dwordx4 v[108:111], v240, s[100:101] offset:512
	s_waitcnt vmcnt(2)
	s_nop 1
	v_mov_b32_e32 v32, v112
	v_mov_b32_e32 v33, v113
	v_mov_b32_e32 v34, v114
	v_mov_b32_e32 v35, v115
	v_mov_b32_e32 v36, v132
	v_mov_b32_e32 v37, v133
	v_mov_b32_e32 v38, v134
	v_mov_b32_e32 v39, v135
	s_cbranch_execz .LBB0_1094
	s_branch .LBB0_1095

.LBB0_1095:
	v_mov_b32_e32 v132, 0x358637bd
	s_waitcnt lgkmcnt(0)
	v_fmac_f32_e32 v132, 0x3a800000, v150
	s_mov_b32 s8, 0x800000
	v_mul_f32_e32 v133, 0x4b800000, v132
	v_cmp_gt_f32_e32 vcc, s8, v132
	v_lshl_add_u64 v[134:135], v[148:149], 1, s[16:17]
	s_nop 0
	v_cndmask_b32_e32 v132, v132, v133, vcc
	v_rsq_f32_e32 v132, v132
	s_nop 0
	v_mul_f32_e32 v133, 0x45800000, v132
	v_cndmask_b32_e32 v132, v132, v133, vcc
	v_pk_mul_f32 v[28:29], v[28:29], v[132:133] op_sel_hi:[1,0]
	v_pk_mul_f32 v[30:31], v[30:31], v[132:133] op_sel_hi:[1,0]
	v_pk_mul_f32 v[24:25], v[24:25], v[132:133] op_sel_hi:[1,0]
	v_pk_mul_f32 v[26:27], v[26:27], v[132:133] op_sel_hi:[1,0]
	s_nop 0
	v_pk_fma_f32 v[38:39], v[182:183], v[30:31], v[38:39]
	v_pk_fma_f32 v[36:37], v[180:181], v[28:29], v[36:37]
	v_pk_fma_f32 v[34:35], v[178:179], v[26:27], v[34:35]
	v_pk_fma_f32 v[32:33], v[176:177], v[24:25], v[32:33]
	s_and_b64 vcc, exec, s[6:7]
	v_cvt_pk_bf16_f32 v24, v36, v37
	v_cvt_pk_bf16_f32 v25, v38, v39
	v_cvt_pk_bf16_f32 v26, v32, v33
	v_cvt_pk_bf16_f32 v27, v34, v35
	global_store_dwordx4 v[134:135], v[24:27], off
	s_cbranch_vccnz .LBB0_1097
	s_waitcnt vmcnt(1)
	s_nop 1
	v_mov_b32_e32 v24, v92
	v_mov_b32_e32 v25, v93
	v_mov_b32_e32 v26, v94
	v_mov_b32_e32 v27, v95
	v_mov_b32_e32 v28, v108
	v_mov_b32_e32 v29, v109
	v_mov_b32_e32 v30, v110
	v_mov_b32_e32 v31, v111
	v_mov_b32_e32 v133, v132
	s_cbranch_execz .LBB0_1098
	s_branch .LBB0_1099

.LBB0_1099:
	v_mov_b32_e32 v112, v132
	v_mov_b32_e32 v113, v132
	v_pk_mul_f32 v[22:23], v[22:23], v[112:113]
	v_pk_mul_f32 v[20:21], v[20:21], v[132:133]
	v_pk_mul_f32 v[18:19], v[18:19], v[112:113]
	v_pk_mul_f32 v[16:17], v[16:17], v[132:133]
	s_nop 0
	v_pk_fma_f32 v[30:31], v[170:171], v[22:23], v[30:31]
	v_pk_fma_f32 v[28:29], v[168:169], v[20:21], v[28:29]
	v_pk_fma_f32 v[26:27], v[166:167], v[18:19], v[26:27]
	v_pk_fma_f32 v[112:113], v[164:165], v[16:17], v[24:25]
	v_cvt_pk_bf16_f32 v16, v28, v29
	v_cvt_pk_bf16_f32 v17, v30, v31
	v_add_u32_e32 v24, 0xb0, v218
	v_cvt_pk_bf16_f32 v18, v112, v113
	v_cvt_pk_bf16_f32 v19, v26, v27
	global_store_dwordx4 v[134:135], v[16:19], off offset:256
	ds_read_b32 v134, v233 offset:8896
	v_ashrrev_i32_e32 v25, 31, v24
	v_lshlrev_b64 v[16:17], 10, v[24:25]
	v_lshl_add_u64 v[114:115], v[16:17], 0, v[216:217]
	s_and_b64 vcc, exec, s[6:7]
	v_lshl_add_u64 v[132:133], v[114:115], 2, s[14:15]
	s_cbranch_vccnz .LBB0_1101
	global_load_dwordx4 v[16:19], v[132:133], off offset:16
	global_load_dwordx4 v[20:23], v[132:133], off
	s_cbranch_execz .LBB0_1102
	s_branch .LBB0_1103
